# scan: L2 prefetch extended to the next chunk's dt rows and the wave's x rows (5 LDS-DMA dword loads per wave in l-tile 5)
# baseline (speedup 1.0000x reference)
; #define LAS __attribute__((address_space(3)))
; template <int MODE> __device__ __forceinline__ void ssd_scan_phase(Frame& F, int j, bool ctx_out) {
;     ...
;                     const int l = 16 * lt + fr; const float cl = tab[l];
;                     f32x4 accd[2], acco[2];
;                     accd[0] = accd[1] = acco[0] = acco[1] = (f32x4){0.f, 0.f, 0.f, 0.f};
;                     const int kd = lt >> 1;
;                     if ((lt & 1) == 0) { xb_cur = xb_nxt; if (kd + 1 < 4) xb_nxt = *(const bf16x8*)(xl + (size_t)16 * T + 32 * (kd + 1)); }
;                     const bf16x8 xa = xf[0][kd], xb = xb_cur;
; #pragma unroll
;                     for (int ks = 0; ks < 4; ++ks) {
;                         const bool full = dir == 0 ? (ks < kd) : (ks > kd);
;                         if (full) {
;                             const bf16x8 gf = *(const LAS bf16x8*)(GS + l * 256 + (((4 * ks + fq) ^ fr) << 4));
;                             const float f1 = __builtin_amdgcn_exp2f(cl - tab[dir == 0 ? 32 * ks + 31 : 32 * ks]);
;                             const f32x4 z4 = (f32x4){0.f, 0.f, 0.f, 0.f};
;                             const f32x4 t0 = __builtin_amdgcn_mfma_f32_16x16x32_bf16(xs2[0][ks], gf, z4, 0, 0, 0), t1 = __builtin_amdgcn_mfma_f32_16x16x32_bf16(xs2[1][ks], gf, z4, 0, 0, 0);
;                             accd[0] += t0 * f1; accd[1] += t1 * f1;
;                         }
;                     }
; #pragma unroll
;                     for (int q = 0; q < 4; ++q) {
;                         const u32x2 lo = *(const LAS u32x2*)(CS + l * 256 + (((4 * q + (fq >> 1)) ^ fr) << 4) + (fq & 1) * 8), hi = *(const LAS u32x2*)(CS + l * 256 + (((4 * q + 2 + (fq >> 1)) ^ fr) << 4) + (fq & 1) * 8);
;                         u32x4 c4; c4.x = lo.x; c4.y = lo.y; c4.z = hi.x; c4.w = hi.y; const bf16x8 cfr = __builtin_bit_cast(bf16x8, c4);
;                         acco[0] = __builtin_amdgcn_mfma_f32_16x16x32_bf16(hf[0][q], cfr, acco[0], 0, 0, 0);
;                         acco[1] = __builtin_amdgcn_mfma_f32_16x16x32_bf16(hf[1][q], cfr, acco[1], 0, 0, 0);
;                     }
;     ...
;                 const int kn = k + 1; const bool isctxn = kn < 2; const int ccn = isctxn ? (dir == 0 ? kn : 1 - kn) : (dir == 0 ? kn - 2 : 17 - kn);
;                 const int row0n = isctxn ? MLAT + b * LCTX + ccn * 128 : b * LSEQ + ccn * 128;
.LBB0_514:
	v_mbcnt_lo_u32_b32 v179, -1, 0
	v_mbcnt_hi_u32_b32 v179, -1, v179
	s_sub_i32 s100, s4, 1
	s_sub_i32 s101, 16, s4
	s_cmp_lg_u32 s38, 0
	s_cselect_b32 s101, s100, s101
	s_lshl_b32 s100, s101, 7
	s_add_i32 s100, s100, s81
	s_cmp_eq_u32 s4, 0
	s_cselect_b32 s100, s76, s100
	s_cselect_b32 s101, 0, s101
	s_cmp_eq_u32 s4, 17
	s_cselect_b32 s100, s81, s100
	s_cselect_b32 s101, 0, s101
	v_and_b32_e32 v178, 3, v179
	v_lshl_add_u32 v178, v178, 5, v188
	v_and_b32_e32 v220, 4, v179
	v_lshlrev_b32_e32 v178, 11, v178
	v_lshl_add_u32 v178, v220, 5, v178
	v_add_u32_e32 v221, s100, v179
	v_lshlrev_b32_e32 v221, 9, v221
	s_lshl_b32 s100, s100, 11
	v_add_u32_e32 v178, s100, v178
	v_lshrrev_b32_e32 v220, 1, v179
	v_and_b32_e32 v179, 1, v179
	v_lshlrev_b32_e32 v220, 12, v220
	v_lshl_add_u32 v220, v179, 7, v220
	s_lshl_b32 s101, s101, 8
	v_add_u32_e32 v220, s101, v220
	v_add_u32_e32 v179, 0x8000, v221
	s_mov_b32 m0, 0x1c000
	s_mov_b32 s100, s77
	s_mov_b32 s101, s73
	global_load_lds_dword v178, s[100:101]
	global_load_lds_dword v178, s[74:75]
	global_load_lds_dword v221, s[34:35]
	global_load_lds_dword v179, s[34:35]
	global_load_lds_dword v220, s[96:97]
	v_add3_u32 v178, 0, v218, v195
	v_add_u32_e32 v179, v178, v185
	ds_read_b64 v[218:219], v179
	v_add_u32_e32 v179, v178, v183
	ds_read_b64 v[220:221], v179
	v_add_u32_e32 v179, v178, v187
	ds_read_b64 v[226:227], v179
	v_add_u32_e32 v179, v178, v213
	ds_read_b64 v[228:229], v179
	s_waitcnt lgkmcnt(2)
	v_mfma_f32_16x16x32_bf16 v[222:225], v[116:119], v[218:221], 0
	v_add_u32_e32 v179, v178, v212
	ds_read_b64 v[230:231], v179
	v_add_u32_e32 v179, v178, v211
	v_mfma_f32_16x16x32_bf16 v[218:221], v[124:127], v[218:221], 0
	ds_read_b64 v[232:233], v179
	v_add_u32_e32 v179, v178, v191
	v_add_u32_e32 v178, v178, v210
	s_waitcnt lgkmcnt(2)
	v_mfma_f32_16x16x32_bf16 v[222:225], v[112:115], v[226:229], v[222:225]
	v_add_u32_e32 v170, v170, v168
	v_sub_f32_e32 v164, v171, v164
	v_exp_f32_e32 v164, v164
	v_mfma_f32_16x16x32_bf16 v[218:221], v[120:123], v[226:229], v[218:221]
	ds_read_b64 v[226:227], v179
	ds_read_b64 v[228:229], v178
	v_sub_f32_e32 v165, v171, v165
	s_waitcnt lgkmcnt(2)
	v_mfma_f32_16x16x32_bf16 v[222:225], v[108:111], v[230:233], v[222:225]
	v_exp_f32_e32 v165, v165
	v_sub_f32_e32 v166, v171, v166
	v_exp_f32_e32 v166, v166
	v_mfma_f32_16x16x32_bf16 v[218:221], v[128:131], v[230:233], v[218:221]
	ds_read_b128 v[230:233], v170
	v_add_u32_e32 v170, 64, v180
	s_waitcnt lgkmcnt(1)
	v_mfma_f32_16x16x32_bf16 v[222:225], v[104:107], v[226:229], v[222:225]
	s_waitcnt lgkmcnt(0)
; #define LAS __attribute__((address_space(3)))
; __device__ __forceinline__ unsigned cvt_pk_bf16(float lo, float hi) { const f32x2 v = {lo, hi}; return __builtin_bit_cast(unsigned, __builtin_convertvector(v, bf16x2_t)); }
; __device__ __forceinline__ u32x4 pack8(const float (&f)[8]) { u32x4 w; w.x = cvt_pk_bf16(f[0], f[1]); w.y = cvt_pk_bf16(f[2], f[3]); w.z = cvt_pk_bf16(f[4], f[5]); w.w = cvt_pk_bf16(f[6], f[7]); return w; }
; template <int MODE> __device__ __forceinline__ void ssd_scan_phase(Frame& F, int j, bool ctx_out) {
;     ...
;                         float gg[8]; unpack8(*(const LAS u32x4*)(GS + l * 256 + (((4 * kd + fq) ^ fr) << 4)), gg);
;                         const f32x4 ca = *(const LAS f32x4*)(tab + 32 * kd + 8 * fq), cb = *(const LAS f32x4*)(tab + 32 * kd + 8 * fq + 4);
;                         const f32x4 da = *(const LAS f32x4*)(tab + 128 + 32 * kd + 8 * fq), db = *(const LAS f32x4*)(tab + 128 + 32 * kd + 8 * fq + 4);
;                         const float cs[8] = {ca.x, ca.y, ca.z, ca.w, cb.x, cb.y, cb.z, cb.w}, ds[8] = {da.x, da.y, da.z, da.w, db.x, db.y, db.z, db.w};
;                         float m[8];
; #pragma unroll
;                         for (int jj = 0; jj < 8; ++jj) { const int s = 32 * kd + 8 * fq + jj; const bool valid = dir == 0 ? (s <= l) : (s >= l);
;                             const float e = valid ? __builtin_amdgcn_exp2f(cl - cs[jj]) : 0.f; m[jj] = gg[jj] * e * ds[jj]; if (dir == 0 && s == l) m[jj] += dsk; }
;                         const bf16x8 mf = __builtin_bit_cast(bf16x8, pack8(m));
;                         accd[0] = __builtin_amdgcn_mfma_f32_16x16x32_bf16(xa, mf, accd[0], 0, 0, 0);
;                         accd[1] = __builtin_amdgcn_mfma_f32_16x16x32_bf16(xb, mf, accd[1], 0, 0, 0);
;                     }
;                     const float el = __builtin_amdgcn_exp2f(cl);
; #pragma unroll
;                     for (int pt = 0; pt < 2; ++pt) { const f32x4 y = accd[pt] + acco[pt] * el; u32x2 o; o.x = cvt_pk_bf16(y[0], y[1]); o.y = cvt_pk_bf16(y[2], y[3]);
;                         *(u32x2*)(yout + (size_t)(row0 + l) * DI + h * 64 + ph * 32 + 16 * pt + 4 * fq) = o; }
;                 }
	v_lshlrev_b32_e32 v178, 16, v230
	v_and_b32_e32 v179, 0xffff0000, v230
	v_lshlrev_b32_e32 v230, 16, v233
	v_mfma_f32_16x16x32_bf16 v[218:221], v[132:135], v[226:229], v[218:221]
	v_lshlrev_b32_e32 v226, 16, v231
	v_and_b32_e32 v227, 0xffff0000, v231
	v_lshlrev_b32_e32 v228, 16, v232
	v_and_b32_e32 v229, 0xffff0000, v232
	v_and_b32_e32 v231, 0xffff0000, v233
	v_cmp_le_i32_e32 vcc, v170, v169
	v_cmp_eq_u32_e64 s[100:101], v170, v169
	s_xnor_b64 vcc, vcc, s[38:39]
	s_andn2_b64 s[100:101], s[100:101], s[38:39]
	s_or_b64 vcc, vcc, s[100:101]
	v_sub_f32_e32 v156, v171, v156
	v_cndmask_b32_e32 v164, 0, v164, vcc
	v_mul_f32_e32 v164, v164, v178
	v_cmp_eq_u32_e32 vcc, v170, v169
	v_mul_f32_e32 v178, v160, v164
	s_and_b64 vcc, s[38:39], vcc
	v_fma_f32 v160, v160, v164, v203
	v_cndmask_b32_e32 v160, v178, v160, vcc
	v_cmp_le_i32_e32 vcc, v173, v169
	v_cmp_eq_u32_e64 s[100:101], v173, v169
	s_xnor_b64 vcc, vcc, s[38:39]
	s_andn2_b64 s[100:101], s[100:101], s[38:39]
	s_or_b64 vcc, vcc, s[100:101]
	v_exp_f32_e32 v156, v156
	v_sub_f32_e32 v157, v171, v157
	v_cndmask_b32_e32 v164, 0, v165, vcc
	v_mul_f32_e32 v164, v164, v179
	v_cmp_eq_u32_e32 vcc, v173, v169
	v_mul_f32_e32 v165, v161, v164
	s_and_b64 vcc, s[38:39], vcc
	v_fma_f32 v161, v161, v164, v203
	v_cndmask_b32_e32 v161, v165, v161, vcc
	v_cmp_le_i32_e32 vcc, v174, v169
	v_cmp_eq_u32_e64 s[100:101], v174, v169
	s_xnor_b64 vcc, vcc, s[38:39]
	s_andn2_b64 s[100:101], s[100:101], s[38:39]
	s_or_b64 vcc, vcc, s[100:101]
	v_exp_f32_e32 v157, v157
	v_sub_f32_e32 v158, v171, v158
	v_cndmask_b32_e32 v164, 0, v166, vcc
	v_mul_f32_e32 v164, v164, v226
	v_cmp_eq_u32_e32 vcc, v174, v169
	v_mul_f32_e32 v165, v162, v164
	s_and_b64 vcc, s[38:39], vcc
	v_fma_f32 v162, v162, v164, v203
	v_cndmask_b32_e32 v162, v165, v162, vcc
	v_sub_f32_e32 v166, v171, v167
	v_exp_f32_e32 v166, v166
	v_cmp_le_i32_e32 vcc, v175, v169
	v_cmp_eq_u32_e64 s[100:101], v175, v169
	s_xnor_b64 vcc, vcc, s[38:39]
	s_andn2_b64 s[100:101], s[100:101], s[38:39]
	s_or_b64 vcc, vcc, s[100:101]
	v_exp_f32_e32 v158, v158
	v_cndmask_b32_e32 v164, 0, v166, vcc
	v_mul_f32_e32 v164, v164, v227
	v_cmp_eq_u32_e32 vcc, v175, v169
	v_mul_f32_e32 v165, v163, v164
	s_and_b64 vcc, s[38:39], vcc
	v_fma_f32 v163, v163, v164, v203
	v_cndmask_b32_e32 v163, v165, v163, vcc
	v_cmp_le_i32_e32 vcc, v200, v169
	v_cmp_eq_u32_e64 s[100:101], v200, v169
	s_xnor_b64 vcc, vcc, s[38:39]
	s_andn2_b64 s[100:101], s[100:101], s[38:39]
	s_or_b64 vcc, vcc, s[100:101]
	s_mov_b32 s94, s92
	s_mov_b32 s95, s92
	v_cndmask_b32_e32 v156, 0, v156, vcc
	v_mul_f32_e32 v156, v156, v228
	v_cmp_eq_u32_e32 vcc, v200, v169
	v_mul_f32_e32 v164, v152, v156
	s_and_b64 vcc, s[38:39], vcc
	v_fma_f32 v152, v152, v156, v203
	v_cndmask_b32_e32 v156, v164, v152, vcc
	v_cmp_le_i32_e32 vcc, v201, v169
	v_cmp_eq_u32_e64 s[100:101], v201, v169
	s_xnor_b64 vcc, vcc, s[38:39]
	s_andn2_b64 s[100:101], s[100:101], s[38:39]
	s_or_b64 vcc, vcc, s[100:101]
	s_mov_b32 s93, s92
	s_nop 0
	v_cndmask_b32_e32 v152, 0, v157, vcc
	v_mul_f32_e32 v152, v152, v229
	v_cmp_eq_u32_e32 vcc, v201, v169
	v_mul_f32_e32 v157, v153, v152
	s_and_b64 vcc, s[38:39], vcc
	v_fma_f32 v152, v153, v152, v203
	v_cndmask_b32_e32 v157, v157, v152, vcc
	v_cmp_le_i32_e32 vcc, v216, v169
	v_cmp_eq_u32_e64 s[100:101], v216, v169
	s_xnor_b64 vcc, vcc, s[38:39]
	s_andn2_b64 s[100:101], s[100:101], s[38:39]
	s_or_b64 vcc, vcc, s[100:101]
	v_cndmask_b32_e32 v152, 0, v158, vcc
	v_mul_f32_e32 v152, v152, v230
	v_cmp_eq_u32_e32 vcc, v216, v169
	v_mul_f32_e32 v153, v154, v152
	s_and_b64 vcc, s[38:39], vcc
	v_fma_f32 v152, v154, v152, v203
	v_cndmask_b32_e32 v158, v153, v152, vcc
	v_sub_f32_e32 v154, v171, v159
	v_exp_f32_e32 v154, v154
	v_cmp_le_i32_e32 vcc, v217, v169
	v_cmp_eq_u32_e64 s[100:101], v217, v169
	s_xnor_b64 vcc, vcc, s[38:39]
	s_andn2_b64 s[100:101], s[100:101], s[38:39]
	s_or_b64 vcc, vcc, s[100:101]
	v_cndmask_b32_e32 v152, 0, v154, vcc
	v_mul_f32_e32 v152, v152, v231
	v_cmp_eq_u32_e32 vcc, v217, v169
	v_mul_f32_e32 v153, v155, v152
	s_and_b64 vcc, s[38:39], vcc
	v_fma_f32 v152, v155, v152, v203
	v_cndmask_b32_e32 v155, v153, v152, vcc
	v_cvt_pk_bf16_f32 v152, v160, v161
	v_cvt_pk_bf16_f32 v153, v162, v163
	v_cvt_pk_bf16_f32 v154, v156, v157
	v_cvt_pk_bf16_f32 v155, v158, v155
	ds_read_b32 v161, v214 offset:384
	v_or_b32_e32 v160, 0x60, v176
	v_mfma_f32_16x16x32_bf16 v[144:147], v[100:103], v[152:155], v[144:147]
	v_mov_b64_e32 v[102:103], s[94:95]
	v_mov_b64_e32 v[100:101], s[92:93]
	s_and_b64 vcc, exec, s[46:47]
	v_mfma_f32_16x16x32_bf16 v[140:143], v[140:143], v[152:155], v[148:151]
	s_nop 2
	v_exp_f32_e32 v148, v171
	v_add_u32_e32 v150, s5, v169
	v_ashrrev_i32_e32 v151, 31, v150
	v_lshlrev_b64 v[150:151], 13, v[150:151]
	v_pk_fma_f32 v[146:147], v[148:149], v[224:225], v[146:147] op_sel_hi:[0,1,1]
	v_pk_fma_f32 v[144:145], v[148:149], v[222:223], v[144:145] op_sel_hi:[0,1,1]
	v_pk_fma_f32 v[142:143], v[148:149], v[220:221], v[142:143] op_sel_hi:[0,1,1]
	v_pk_fma_f32 v[140:141], v[148:149], v[218:219], v[140:141] op_sel_hi:[0,1,1]
	v_lshl_add_u64 v[150:151], v[198:199], 0, v[150:151]
	v_cvt_pk_bf16_f32 v144, v144, v145
	v_cvt_pk_bf16_f32 v145, v146, v147
	v_cvt_pk_bf16_f32 v140, v140, v141
	v_cvt_pk_bf16_f32 v141, v142, v143
	global_store_dwordx2 v[150:151], v[144:145], off
	global_store_dwordx2 v[150:151], v[140:141], off offset:32
	v_lshlrev_b32_e32 v141, 8, v160
	v_mov_b64_e32 v[150:151], s[94:95]
	v_add_u32_e32 v140, s87, v141
	v_mov_b64_e32 v[148:149], s[92:93]
	s_cbranch_vccz .LBB0_536
	s_and_b64 vcc, exec, s[46:47]
	s_cbranch_vccz .LBB0_537

; #define LAS __attribute__((address_space(3)))
; template <int MODE> __device__ __forceinline__ void ssd_scan_phase(Frame& F, int j, bool ctx_out) {
;     ...
;                     const int l = 16 * lt + fr; const float cl = tab[l];
;                     f32x4 accd[2], acco[2];
;                     accd[0] = accd[1] = acco[0] = acco[1] = (f32x4){0.f, 0.f, 0.f, 0.f};
;                     const int kd = lt >> 1;
;                     if ((lt & 1) == 0) { xb_cur = xb_nxt; if (kd + 1 < 4) xb_nxt = *(const bf16x8*)(xl + (size_t)16 * T + 32 * (kd + 1)); }
;                     const bf16x8 xa = xf[0][kd], xb = xb_cur;
; #pragma unroll
;                     for (int ks = 0; ks < 4; ++ks) {
;                         const bool full = dir == 0 ? (ks < kd) : (ks > kd);
;                         if (full) {
;                             const bf16x8 gf = *(const LAS bf16x8*)(GS + l * 256 + (((4 * ks + fq) ^ fr) << 4));
;                             const float f1 = __builtin_amdgcn_exp2f(cl - tab[dir == 0 ? 32 * ks + 31 : 32 * ks]);
;                             const f32x4 z4 = (f32x4){0.f, 0.f, 0.f, 0.f};
;                             const f32x4 t0 = __builtin_amdgcn_mfma_f32_16x16x32_bf16(xs2[0][ks], gf, z4, 0, 0, 0), t1 = __builtin_amdgcn_mfma_f32_16x16x32_bf16(xs2[1][ks], gf, z4, 0, 0, 0);
;                             accd[0] += t0 * f1; accd[1] += t1 * f1;
;                         }
;                     }
; #pragma unroll
;                     for (int q = 0; q < 4; ++q) {
;                         const u32x2 lo = *(const LAS u32x2*)(CS + l * 256 + (((4 * q + (fq >> 1)) ^ fr) << 4) + (fq & 1) * 8), hi = *(const LAS u32x2*)(CS + l * 256 + (((4 * q + 2 + (fq >> 1)) ^ fr) << 4) + (fq & 1) * 8);
;                         u32x4 c4; c4.x = lo.x; c4.y = lo.y; c4.z = hi.x; c4.w = hi.y; const bf16x8 cfr = __builtin_bit_cast(bf16x8, c4);
;                         acco[0] = __builtin_amdgcn_mfma_f32_16x16x32_bf16(hf[0][q], cfr, acco[0], 0, 0, 0);
;                         acco[1] = __builtin_amdgcn_mfma_f32_16x16x32_bf16(hf[1][q], cfr, acco[1], 0, 0, 0);
;                     }
;                     {
;                         float gg[8]; unpack8(*(const LAS u32x4*)(GS + l * 256 + (((4 * kd + fq) ^ fr) << 4)), gg);
;                         const f32x4 ca = *(const LAS f32x4*)(tab + 32 * kd + 8 * fq), cb = *(const LAS f32x4*)(tab + 32 * kd + 8 * fq + 4);
.LBB0_518:
	v_add3_u32 v141, 0, v141, v195
	v_add_u32_e32 v142, v141, v185
	v_add_u32_e32 v144, v141, v183
	ds_read_b64 v[142:143], v142
	ds_read_b64 v[144:145], v144
	v_add_u32_e32 v146, v141, v187
	ds_read_b64 v[152:153], v146
	ds_read_b32 v162, v214 offset:448
	v_add_u32_e32 v146, v141, v213
	ds_read_b64 v[154:155], v146
	s_waitcnt lgkmcnt(3)
	v_mfma_f32_16x16x32_bf16 v[156:159], v[116:119], v[142:145], 0
	v_add_u32_e32 v146, v141, v212
	v_add_u32_e32 v147, v141, v211
	v_add_u32_e32 v163, v141, v191
	v_mfma_f32_16x16x32_bf16 v[142:145], v[124:127], v[142:145], 0
	ds_read_b64 v[164:165], v146
	ds_read_b64 v[166:167], v147
	ds_read_b64 v[216:217], v163
	v_add_u32_e32 v141, v141, v210
	v_lshlrev_b32_e32 v171, 4, v205
	s_waitcnt lgkmcnt(3)
	v_mfma_f32_16x16x32_bf16 v[156:159], v[112:115], v[152:155], v[156:159]
	ds_read_b64 v[218:219], v141
	v_add_u32_e32 v140, v140, v171
	v_add_u32_e32 v170, 0x61, v180
	v_mfma_f32_16x16x32_bf16 v[142:145], v[120:123], v[152:155], v[142:145]
	v_add_u32_e32 v169, 0x62, v180
	s_mov_b32 s94, s92
	s_waitcnt lgkmcnt(2)
	v_mfma_f32_16x16x32_bf16 v[152:155], v[108:111], v[164:167], v[156:159]
	s_mov_b32 s95, s92
	s_mov_b32 s93, s92
	s_nop 0
	ds_read_b128 v[156:159], v197 offset:384
	v_mfma_f32_16x16x32_bf16 v[142:145], v[128:131], v[164:167], v[142:145]
	ds_read_b128 v[164:167], v140
	s_waitcnt lgkmcnt(1)
	v_sub_f32_e32 v140, v161, v156
	v_mfma_f32_16x16x32_bf16 v[220:223], v[104:107], v[216:219], v[152:155]
	s_waitcnt lgkmcnt(0)
	v_lshlrev_b32_e32 v174, 16, v166
	v_and_b32_e32 v175, 0xffff0000, v166
	v_exp_f32_e32 v166, v140
	v_mfma_f32_16x16x32_bf16 v[216:219], v[132:135], v[216:219], v[142:145]
	ds_read_b128 v[152:155], v197 offset:896
	v_lshlrev_b32_e32 v163, 16, v164
	v_cndmask_b32_e64 v166, 0, v166, s[40:41]
	ds_read_b128 v[144:147], v197 offset:400
	v_mul_f32_e32 v163, v166, v163
	s_waitcnt lgkmcnt(1)
	v_mul_f32_e32 v166, v152, v163
	v_fma_f32 v163, v152, v163, v203
	v_lshlrev_b32_e32 v178, 16, v167
	v_and_b32_e32 v179, 0xffff0000, v167
	ds_read_b128 v[140:143], v197 offset:912
	v_cndmask_b32_e64 v197, v166, v163, s[42:43]
	v_sub_f32_e32 v167, v161, v157
	v_exp_f32_e32 v167, v167
	v_cmp_le_i32_e32 vcc, v170, v160
	v_cmp_eq_u32_e64 s[100:101], v170, v160
	s_xnor_b64 vcc, vcc, s[38:39]
	s_andn2_b64 s[100:101], s[100:101], s[38:39]
	s_or_b64 vcc, vcc, s[100:101]
	v_and_b32_e32 v164, 0xffff0000, v164
	v_sub_f32_e32 v166, v161, v158
	v_cndmask_b32_e32 v163, 0, v167, vcc
	v_mul_f32_e32 v163, v163, v164
	v_cmp_eq_u32_e32 vcc, v170, v160
	v_mul_f32_e32 v164, v153, v163
	v_fma_f32 v163, v153, v163, v203
	s_and_b64 vcc, s[38:39], vcc
	v_cndmask_b32_e32 v200, v164, v163, vcc
	v_exp_f32_e32 v166, v166
	v_lshlrev_b32_e32 v173, 16, v165
	v_add_u32_e32 v167, 0x63, v180
	v_and_b32_e32 v165, 0xffff0000, v165
	v_cmp_le_i32_e32 vcc, v169, v160
	v_cmp_eq_u32_e64 s[100:101], v169, v160
	s_xnor_b64 vcc, vcc, s[38:39]
	s_andn2_b64 s[100:101], s[100:101], s[38:39]
	s_or_b64 vcc, vcc, s[100:101]
	s_waitcnt lgkmcnt(1)
	v_sub_f32_e32 v214, v161, v145
	v_exp_f32_e32 v214, v214
	v_cndmask_b32_e32 v163, 0, v166, vcc
	v_mul_f32_e32 v163, v163, v173
	v_cmp_eq_u32_e32 vcc, v169, v160
	v_mul_f32_e32 v164, v154, v163
	v_fma_f32 v163, v154, v163, v203
	s_and_b64 vcc, s[38:39], vcc
	v_cndmask_b32_e32 v173, v164, v163, vcc
	v_sub_f32_e32 v166, v161, v159
	v_exp_f32_e32 v166, v166
	v_sub_f32_e32 v224, v161, v146
	v_exp_f32_e32 v224, v224
	v_cmp_le_i32_e32 vcc, v167, v160
	v_cmp_eq_u32_e64 s[100:101], v167, v160
	s_xnor_b64 vcc, vcc, s[38:39]
	s_andn2_b64 s[100:101], s[100:101], s[38:39]
	s_or_b64 vcc, vcc, s[100:101]
	v_sub_f32_e32 v225, v161, v147
	v_exp_f32_e32 v225, v225
	v_cndmask_b32_e32 v163, 0, v166, vcc
	v_mul_f32_e32 v163, v163, v165
	v_cmp_eq_u32_e32 vcc, v167, v160
	v_mul_f32_e32 v164, v155, v163
	v_fma_f32 v163, v155, v163, v203
	s_and_b64 vcc, s[38:39], vcc
	v_add_u32_e32 v166, 0x64, v180
	v_cndmask_b32_e32 v201, v164, v163, vcc
	v_sub_f32_e32 v165, v161, v144
	v_exp_f32_e32 v165, v165
	s_nop 1
	v_cmp_le_i32_e32 vcc, v166, v160
	v_cmp_eq_u32_e64 s[100:101], v166, v160
	s_xnor_b64 vcc, vcc, s[38:39]
	s_andn2_b64 s[100:101], s[100:101], s[38:39]
	s_or_b64 vcc, vcc, s[100:101]
	v_cndmask_b32_e32 v163, 0, v165, vcc
	v_mul_f32_e32 v163, v163, v174
	v_cmp_eq_u32_e32 vcc, v166, v160
	s_waitcnt lgkmcnt(0)
; __device__ __forceinline__ unsigned cvt_pk_bf16(float lo, float hi) { const f32x2 v = {lo, hi}; return __builtin_bit_cast(unsigned, __builtin_convertvector(v, bf16x2_t)); }
; __device__ __forceinline__ u32x4 pack8(const float (&f)[8]) { u32x4 w; w.x = cvt_pk_bf16(f[0], f[1]); w.y = cvt_pk_bf16(f[2], f[3]); w.z = cvt_pk_bf16(f[4], f[5]); w.w = cvt_pk_bf16(f[6], f[7]); return w; }
; template <int MODE> __device__ __forceinline__ void ssd_scan_phase(Frame& F, int j, bool ctx_out) {
;     ...
;                         for (int jj = 0; jj < 8; ++jj) { const int s = 32 * kd + 8 * fq + jj; const bool valid = dir == 0 ? (s <= l) : (s >= l);
;                             const float e = valid ? __builtin_amdgcn_exp2f(cl - cs[jj]) : 0.f; m[jj] = gg[jj] * e * ds[jj]; if (dir == 0 && s == l) m[jj] += dsk; }
;                         const bf16x8 mf = __builtin_bit_cast(bf16x8, pack8(m));
;                         accd[0] = __builtin_amdgcn_mfma_f32_16x16x32_bf16(xa, mf, accd[0], 0, 0, 0);
;                         accd[1] = __builtin_amdgcn_mfma_f32_16x16x32_bf16(xb, mf, accd[1], 0, 0, 0);
;                     }
;                     const float el = __builtin_amdgcn_exp2f(cl);
; #pragma unroll
;                     for (int pt = 0; pt < 2; ++pt) { const f32x4 y = accd[pt] + acco[pt] * el; u32x2 o; o.x = cvt_pk_bf16(y[0], y[1]); o.y = cvt_pk_bf16(y[2], y[3]);
;                         *(u32x2*)(yout + (size_t)(row0 + l) * DI + h * 64 + ph * 32 + 16 * pt + 4 * fq) = o; }
;                 }
	v_mul_f32_e32 v164, v140, v163
	v_fma_f32 v163, v140, v163, v203
	s_and_b64 vcc, s[38:39], vcc
	v_add_u32_e32 v165, 0x65, v180
	v_cndmask_b32_e32 v174, v164, v163, vcc
	s_nop 1
	s_nop 1
	v_cmp_le_i32_e32 vcc, v165, v160
	v_cmp_eq_u32_e64 s[100:101], v165, v160
	s_xnor_b64 vcc, vcc, s[38:39]
	s_andn2_b64 s[100:101], s[100:101], s[38:39]
	s_or_b64 vcc, vcc, s[100:101]
	v_cndmask_b32_e32 v163, 0, v214, vcc
	v_mul_f32_e32 v163, v163, v175
	v_cmp_eq_u32_e32 vcc, v165, v160
	v_mul_f32_e32 v164, v141, v163
	v_fma_f32 v163, v141, v163, v203
	s_and_b64 vcc, s[38:39], vcc
	v_cndmask_b32_e32 v175, v164, v163, vcc
	v_add_u32_e32 v164, 0x66, v180
	v_cvt_pk_bf16_f32 v226, v174, v175
	v_exp_f32_e32 v174, v161
	s_nop 1
	v_cmp_le_i32_e32 vcc, v164, v160
	v_cmp_eq_u32_e64 s[100:101], v164, v160
	s_xnor_b64 vcc, vcc, s[38:39]
	s_andn2_b64 s[100:101], s[100:101], s[38:39]
	s_or_b64 vcc, vcc, s[100:101]
	v_cndmask_b32_e32 v163, 0, v224, vcc
	v_mul_f32_e32 v163, v163, v178
	v_cmp_eq_u32_e32 vcc, v164, v160
	v_mul_f32_e32 v178, v142, v163
	v_fma_f32 v163, v142, v163, v203
	s_and_b64 vcc, s[38:39], vcc
	v_cndmask_b32_e32 v178, v178, v163, vcc
	v_add_u32_e32 v163, 0x67, v180
	s_nop 1
	s_nop 1
	v_cmp_le_i32_e32 vcc, v163, v160
	v_cmp_eq_u32_e64 s[100:101], v163, v160
	s_xnor_b64 vcc, vcc, s[38:39]
	s_andn2_b64 s[100:101], s[100:101], s[38:39]
	s_or_b64 vcc, vcc, s[100:101]
	v_cvt_pk_bf16_f32 v224, v197, v200
	s_nop 0
	v_cndmask_b32_e32 v214, 0, v225, vcc
	v_mul_f32_e32 v179, v214, v179
	v_cmp_eq_u32_e32 vcc, v163, v160
	v_mul_f32_e32 v214, v143, v179
	v_fma_f32 v179, v143, v179, v203
	s_and_b64 vcc, s[38:39], vcc
	v_cndmask_b32_e32 v179, v214, v179, vcc
	v_cvt_pk_bf16_f32 v225, v173, v201
	v_cvt_pk_bf16_f32 v227, v178, v179
	v_add_u32_e32 v160, s5, v160
	v_ashrrev_i32_e32 v161, 31, v160
	v_mfma_f32_16x16x32_bf16 v[228:231], v[8:11], v[224:227], v[148:151]
	v_lshlrev_b64 v[160:161], 13, v[160:161]
	v_lshl_add_u64 v[160:161], v[198:199], 0, v[160:161]
	s_and_b64 vcc, exec, s[46:47]
	s_waitcnt vmcnt(9)
	v_mfma_f32_16x16x32_bf16 v[100:103], v[136:139], v[224:227], v[100:103]
	v_mov_b64_e32 v[150:151], s[94:95]
	s_nop 1
	v_pk_fma_f32 v[200:201], v[174:175], v[222:223], v[230:231] op_sel_hi:[0,1,1]
	v_pk_fma_f32 v[220:221], v[174:175], v[220:221], v[228:229] op_sel_hi:[0,1,1]
	v_cvt_pk_bf16_f32 v220, v220, v221
	v_cvt_pk_bf16_f32 v221, v200, v201
	s_nop 0
	v_pk_fma_f32 v[102:103], v[174:175], v[218:219], v[102:103] op_sel_hi:[0,1,1]
	v_pk_fma_f32 v[100:101], v[174:175], v[216:217], v[100:101] op_sel_hi:[0,1,1]
	v_cvt_pk_bf16_f32 v100, v100, v101
	v_cvt_pk_bf16_f32 v101, v102, v103
	global_store_dwordx2 v[160:161], v[220:221], off
	global_store_dwordx2 v[160:161], v[100:101], off offset:32
	v_or_b32_e32 v160, 0x70, v176
	v_lshlrev_b32_e32 v173, 8, v160
	v_mov_b64_e32 v[102:103], s[94:95]
	v_mov_b64_e32 v[148:149], s[92:93]
	v_add_u32_e32 v161, s87, v173
	v_mov_b64_e32 v[100:101], s[92:93]
	s_cbranch_vccz .LBB0_538
	s_and_b64 vcc, exec, s[46:47]
	s_cbranch_vccz .LBB0_539
